# at the three seams that follow a norm phase wave 1 issues the L1 invalidate right after its last stores (draining with vmcnt(1)), so the invalidate overlaps the store drain and the next GEMM's set-up
# baseline (speedup 1.0000x reference)
.Lnorm0_done:
.LBB0_280:
	s_or_b64 exec, exec, s[16:17]
	s_mov_b64 s[8:9], s[0:1]
	v_readfirstlane_b32 s100, v147
	s_nop 0
	s_cmp_eq_u32 s100, 64
	s_cbranch_scc0 .Lei_std_1
	buffer_inv sc1
	s_waitcnt vmcnt(1)
	s_branch .Lei_done_1

.Lei_done_1:
	v_mov_b32_e32 v0, v147
	s_barrier
	s_nop 0
	v_readfirstlane_b32 vcc_lo, v0
	s_nop 1
	s_cmp_eq_u32 vcc_lo, 64
	s_cbranch_scc0 .Lxb_noinv_1

.LBB0_523:
	s_or_b64 exec, exec, s[8:9]
	v_readfirstlane_b32 s100, v147
	s_nop 0
	s_cmp_eq_u32 s100, 64
	s_cbranch_scc0 .Lei_std_4
	buffer_inv sc1
	s_waitcnt vmcnt(1)
	s_branch .Lei_done_4

.LBB0_1225:
	s_or_b64 exec, exec, s[10:11]
	v_readfirstlane_b32 s100, v147
	s_nop 0
	s_cmp_eq_u32 s100, 64
	s_cbranch_scc0 .Lei_std_8
	buffer_inv sc1
	s_waitcnt vmcnt(1)
	s_branch .Lei_done_8
